# GEMM K-loops: the four LDS-DMA pieces of each step issued interleaved between MFMA groups instead of ahead of them
# speedup vs baseline: 1.0037x; 1.0037x over previous
.Lg1_ndw0:
.Lg1_swdw0:
	s_add_i32 s25, s25, 1
	v_add_u32_e32 v244, s28, v242
	v_add_u32_e32 v245, s28, v243
	ds_read_b128 v[198:201], v244 offset:0
	ds_read_b128 v[202:205], v244 offset:2048
	ds_read_b128 v[210:213], v244 offset:4096
	ds_read_b128 v[214:217], v244 offset:6144
	ds_read_b128 v[218:221], v244 offset:8192
	ds_read_b128 v[222:225], v244 offset:10240
	ds_read_b128 v[226:229], v244 offset:12288
	ds_read_b128 v[230:233], v244 offset:14336
	s_waitcnt lgkmcnt(4)
	s_add_i32 m0, s27, s97
	v_mfma_f32_16x16x32_bf16 v[0:3], v[128:131], v[198:201], v[0:3]
	v_mfma_f32_16x16x32_bf16 v[32:35], v[132:135], v[198:201], v[32:35]
	v_mfma_f32_16x16x32_bf16 v[64:67], v[136:139], v[198:201], v[64:67]
	v_mfma_f32_16x16x32_bf16 v[96:99], v[140:143], v[198:201], v[96:99]
	global_load_lds_dwordx4 v234, s[58:59]
	s_add_i32 m0, m0, 0x400
	v_mfma_f32_16x16x32_bf16 v[4:7], v[128:131], v[202:205], v[4:7]
	v_mfma_f32_16x16x32_bf16 v[36:39], v[132:135], v[202:205], v[36:39]
	v_mfma_f32_16x16x32_bf16 v[68:71], v[136:139], v[202:205], v[68:71]
	v_mfma_f32_16x16x32_bf16 v[100:103], v[140:143], v[202:205], v[100:103]
	global_load_lds_dwordx4 v235, s[58:59]
	s_add_i32 m0, m0, 0x400
	v_mfma_f32_16x16x32_bf16 v[8:11], v[128:131], v[210:213], v[8:11]
	v_mfma_f32_16x16x32_bf16 v[40:43], v[132:135], v[210:213], v[40:43]
	v_mfma_f32_16x16x32_bf16 v[72:75], v[136:139], v[210:213], v[72:75]
	v_mfma_f32_16x16x32_bf16 v[104:107], v[140:143], v[210:213], v[104:107]
	global_load_lds_dwordx4 v236, s[58:59]
	s_add_i32 m0, m0, 0x400
	v_mfma_f32_16x16x32_bf16 v[12:15], v[128:131], v[214:217], v[12:15]
	v_mfma_f32_16x16x32_bf16 v[44:47], v[132:135], v[214:217], v[44:47]
	v_mfma_f32_16x16x32_bf16 v[76:79], v[136:139], v[214:217], v[76:79]
	v_mfma_f32_16x16x32_bf16 v[108:111], v[140:143], v[214:217], v[108:111]
	global_load_lds_dwordx4 v237, s[58:59]
	s_cmp_eq_u32 s29, 13
	s_cbranch_scc1 .Lg1_saa1
	s_add_u32 s58, s58, 128
	s_addc_u32 s59, s59, 0
	s_branch .Lg1_sada1

.Lg1_nda1:
.Lg1_sada1:
	ds_read_b128 v[198:201], v245 offset:0
	ds_read_b128 v[202:205], v245 offset:2048
	ds_read_b128 v[210:213], v245 offset:4096
	ds_read_b128 v[214:217], v245 offset:6144
	s_waitcnt lgkmcnt(4)
	v_mfma_f32_16x16x32_bf16 v[16:19], v[128:131], v[218:221], v[16:19]
	v_mfma_f32_16x16x32_bf16 v[48:51], v[132:135], v[218:221], v[48:51]
	v_mfma_f32_16x16x32_bf16 v[80:83], v[136:139], v[218:221], v[80:83]
	v_mfma_f32_16x16x32_bf16 v[112:115], v[140:143], v[218:221], v[112:115]
	v_mfma_f32_16x16x32_bf16 v[20:23], v[128:131], v[222:225], v[20:23]
	v_mfma_f32_16x16x32_bf16 v[52:55], v[132:135], v[222:225], v[52:55]
	v_mfma_f32_16x16x32_bf16 v[84:87], v[136:139], v[222:225], v[84:87]
	v_mfma_f32_16x16x32_bf16 v[116:119], v[140:143], v[222:225], v[116:119]
	v_mfma_f32_16x16x32_bf16 v[24:27], v[128:131], v[226:229], v[24:27]
	v_mfma_f32_16x16x32_bf16 v[56:59], v[132:135], v[226:229], v[56:59]
	v_mfma_f32_16x16x32_bf16 v[88:91], v[136:139], v[226:229], v[88:91]
	v_mfma_f32_16x16x32_bf16 v[120:123], v[140:143], v[226:229], v[120:123]
	v_mfma_f32_16x16x32_bf16 v[28:31], v[128:131], v[230:233], v[28:31]
	v_mfma_f32_16x16x32_bf16 v[60:63], v[132:135], v[230:233], v[60:63]
	v_mfma_f32_16x16x32_bf16 v[92:95], v[136:139], v[230:233], v[92:95]
	v_mfma_f32_16x16x32_bf16 v[124:127], v[140:143], v[230:233], v[124:127]
	ds_read_b128 v[218:221], v245 offset:8192
	ds_read_b128 v[222:225], v245 offset:10240
	ds_read_b128 v[226:229], v245 offset:12288
	ds_read_b128 v[230:233], v245 offset:14336
	s_waitcnt vmcnt(16)
	global_load_dwordx4 v[128:131], v238, s[56:57]
	global_load_dwordx4 v[132:135], v239, s[56:57]
	global_load_dwordx4 v[136:139], v240, s[56:57]
	global_load_dwordx4 v[140:143], v241, s[56:57]
	s_cmp_eq_u32 s25, 31
	s_cbranch_scc1 .Lg1_sww2
	s_add_u32 s56, s56, 1024
	s_addc_u32 s57, s57, 0
	s_branch .Lg1_swdw2

.Lg1_ndw3:
.Lg1_swdw3:
	s_add_i32 s25, s25, 1
	v_add_u32_e32 v244, s28, v242
	v_add_u32_e32 v245, s28, v243
	ds_read_b128 v[198:201], v244 offset:0
	ds_read_b128 v[202:205], v244 offset:2048
	ds_read_b128 v[210:213], v244 offset:4096
	ds_read_b128 v[214:217], v244 offset:6144
	ds_read_b128 v[218:221], v244 offset:8192
	ds_read_b128 v[222:225], v244 offset:10240
	ds_read_b128 v[226:229], v244 offset:12288
	ds_read_b128 v[230:233], v244 offset:14336
	s_waitcnt lgkmcnt(4)
	s_add_i32 m0, s27, s97
	v_mfma_f32_16x16x32_bf16 v[0:3], v[160:163], v[198:201], v[0:3]
	v_mfma_f32_16x16x32_bf16 v[32:35], v[164:167], v[198:201], v[32:35]
	v_mfma_f32_16x16x32_bf16 v[64:67], v[168:171], v[198:201], v[64:67]
	v_mfma_f32_16x16x32_bf16 v[96:99], v[172:175], v[198:201], v[96:99]
	global_load_lds_dwordx4 v234, s[58:59]
	s_add_i32 m0, m0, 0x400
	v_mfma_f32_16x16x32_bf16 v[4:7], v[160:163], v[202:205], v[4:7]
	v_mfma_f32_16x16x32_bf16 v[36:39], v[164:167], v[202:205], v[36:39]
	v_mfma_f32_16x16x32_bf16 v[68:71], v[168:171], v[202:205], v[68:71]
	v_mfma_f32_16x16x32_bf16 v[100:103], v[172:175], v[202:205], v[100:103]
	global_load_lds_dwordx4 v235, s[58:59]
	s_add_i32 m0, m0, 0x400
	v_mfma_f32_16x16x32_bf16 v[8:11], v[160:163], v[210:213], v[8:11]
	v_mfma_f32_16x16x32_bf16 v[40:43], v[164:167], v[210:213], v[40:43]
	v_mfma_f32_16x16x32_bf16 v[72:75], v[168:171], v[210:213], v[72:75]
	v_mfma_f32_16x16x32_bf16 v[104:107], v[172:175], v[210:213], v[104:107]
	global_load_lds_dwordx4 v236, s[58:59]
	s_add_i32 m0, m0, 0x400
	v_mfma_f32_16x16x32_bf16 v[12:15], v[160:163], v[214:217], v[12:15]
	v_mfma_f32_16x16x32_bf16 v[44:47], v[164:167], v[214:217], v[44:47]
	v_mfma_f32_16x16x32_bf16 v[76:79], v[168:171], v[214:217], v[76:79]
	v_mfma_f32_16x16x32_bf16 v[108:111], v[172:175], v[214:217], v[108:111]
	global_load_lds_dwordx4 v237, s[58:59]
	s_cmp_eq_u32 s29, 13
	s_cbranch_scc1 .Lg1_saa4
	s_add_u32 s58, s58, 128
	s_addc_u32 s59, s59, 0
	s_branch .Lg1_sada4

.Lg1_nda4:
.Lg1_sada4:
	ds_read_b128 v[198:201], v245 offset:0
	ds_read_b128 v[202:205], v245 offset:2048
	ds_read_b128 v[210:213], v245 offset:4096
	ds_read_b128 v[214:217], v245 offset:6144
	s_waitcnt lgkmcnt(4)
	v_mfma_f32_16x16x32_bf16 v[16:19], v[160:163], v[218:221], v[16:19]
	v_mfma_f32_16x16x32_bf16 v[48:51], v[164:167], v[218:221], v[48:51]
	v_mfma_f32_16x16x32_bf16 v[80:83], v[168:171], v[218:221], v[80:83]
	v_mfma_f32_16x16x32_bf16 v[112:115], v[172:175], v[218:221], v[112:115]
	v_mfma_f32_16x16x32_bf16 v[20:23], v[160:163], v[222:225], v[20:23]
	v_mfma_f32_16x16x32_bf16 v[52:55], v[164:167], v[222:225], v[52:55]
	v_mfma_f32_16x16x32_bf16 v[84:87], v[168:171], v[222:225], v[84:87]
	v_mfma_f32_16x16x32_bf16 v[116:119], v[172:175], v[222:225], v[116:119]
	v_mfma_f32_16x16x32_bf16 v[24:27], v[160:163], v[226:229], v[24:27]
	v_mfma_f32_16x16x32_bf16 v[56:59], v[164:167], v[226:229], v[56:59]
	v_mfma_f32_16x16x32_bf16 v[88:91], v[168:171], v[226:229], v[88:91]
	v_mfma_f32_16x16x32_bf16 v[120:123], v[172:175], v[226:229], v[120:123]
	v_mfma_f32_16x16x32_bf16 v[28:31], v[160:163], v[230:233], v[28:31]
	v_mfma_f32_16x16x32_bf16 v[60:63], v[164:167], v[230:233], v[60:63]
	v_mfma_f32_16x16x32_bf16 v[92:95], v[168:171], v[230:233], v[92:95]
	v_mfma_f32_16x16x32_bf16 v[124:127], v[172:175], v[230:233], v[124:127]
	ds_read_b128 v[218:221], v245 offset:8192
	ds_read_b128 v[222:225], v245 offset:10240
	ds_read_b128 v[226:229], v245 offset:12288
	ds_read_b128 v[230:233], v245 offset:14336
	s_waitcnt vmcnt(16)
	global_load_dwordx4 v[160:163], v238, s[56:57]
	global_load_dwordx4 v[164:167], v239, s[56:57]
	global_load_dwordx4 v[168:171], v240, s[56:57]
	global_load_dwordx4 v[172:175], v241, s[56:57]
	s_cmp_eq_u32 s25, 31
	s_cbranch_scc1 .Lg1_sww5
	s_add_u32 s56, s56, 1024
	s_addc_u32 s57, s57, 0
	s_branch .Lg1_swdw5

.Lg2_wndw0:
.Lg2_swdw0:
	s_add_i32 s59, s59, 1
	v_add_u32_e32 v244, s56, v242
	v_add_u32_e32 v245, s56, v243
	ds_read_b128 v[200:203], v244 offset:0
	ds_read_b128 v[204:207], v244 offset:2048
	ds_read_b128 v[210:213], v244 offset:4096
	ds_read_b128 v[214:217], v244 offset:6144
	ds_read_b128 v[218:221], v244 offset:8192
	ds_read_b128 v[222:225], v244 offset:10240
	ds_read_b128 v[226:229], v244 offset:12288
	ds_read_b128 v[230:233], v244 offset:14336
	s_waitcnt lgkmcnt(4)
	s_add_i32 m0, s57, s60
	v_mfma_f32_16x16x32_bf16 v[0:3], v[128:131], v[200:203], v[0:3]
	v_mfma_f32_16x16x32_bf16 v[32:35], v[132:135], v[200:203], v[32:35]
	v_mfma_f32_16x16x32_bf16 v[64:67], v[136:139], v[200:203], v[64:67]
	v_mfma_f32_16x16x32_bf16 v[96:99], v[140:143], v[200:203], v[96:99]
	global_load_lds_dwordx4 v234, s[52:53]
	s_add_i32 m0, m0, 0x400
	v_mfma_f32_16x16x32_bf16 v[4:7], v[128:131], v[204:207], v[4:7]
	v_mfma_f32_16x16x32_bf16 v[36:39], v[132:135], v[204:207], v[36:39]
	v_mfma_f32_16x16x32_bf16 v[68:71], v[136:139], v[204:207], v[68:71]
	v_mfma_f32_16x16x32_bf16 v[100:103], v[140:143], v[204:207], v[100:103]
	global_load_lds_dwordx4 v235, s[52:53]
	s_add_i32 m0, m0, 0x400
	v_mfma_f32_16x16x32_bf16 v[8:11], v[128:131], v[210:213], v[8:11]
	v_mfma_f32_16x16x32_bf16 v[40:43], v[132:135], v[210:213], v[40:43]
	v_mfma_f32_16x16x32_bf16 v[72:75], v[136:139], v[210:213], v[72:75]
	v_mfma_f32_16x16x32_bf16 v[104:107], v[140:143], v[210:213], v[104:107]
	global_load_lds_dwordx4 v236, s[52:53]
	s_add_i32 m0, m0, 0x400
	v_mfma_f32_16x16x32_bf16 v[12:15], v[128:131], v[214:217], v[12:15]
	v_mfma_f32_16x16x32_bf16 v[44:47], v[132:135], v[214:217], v[44:47]
	v_mfma_f32_16x16x32_bf16 v[76:79], v[136:139], v[214:217], v[76:79]
	v_mfma_f32_16x16x32_bf16 v[108:111], v[140:143], v[214:217], v[108:111]
	global_load_lds_dwordx4 v237, s[52:53]
	s_cmp_eq_u32 s58, 13
	s_cbranch_scc1 .Lg2_saa1
	s_add_u32 s52, s52, 128
	s_addc_u32 s53, s53, 0
	s_branch .Lg2_sada1

.Lg2_nda1:
.Lg2_sada1:
	ds_read_b128 v[200:203], v245 offset:0
	ds_read_b128 v[204:207], v245 offset:2048
	ds_read_b128 v[210:213], v245 offset:4096
	ds_read_b128 v[214:217], v245 offset:6144
	s_waitcnt lgkmcnt(4)
	v_mfma_f32_16x16x32_bf16 v[16:19], v[128:131], v[218:221], v[16:19]
	v_mfma_f32_16x16x32_bf16 v[48:51], v[132:135], v[218:221], v[48:51]
	v_mfma_f32_16x16x32_bf16 v[80:83], v[136:139], v[218:221], v[80:83]
	v_mfma_f32_16x16x32_bf16 v[112:115], v[140:143], v[218:221], v[112:115]
	v_mfma_f32_16x16x32_bf16 v[20:23], v[128:131], v[222:225], v[20:23]
	v_mfma_f32_16x16x32_bf16 v[52:55], v[132:135], v[222:225], v[52:55]
	v_mfma_f32_16x16x32_bf16 v[84:87], v[136:139], v[222:225], v[84:87]
	v_mfma_f32_16x16x32_bf16 v[116:119], v[140:143], v[222:225], v[116:119]
	v_mfma_f32_16x16x32_bf16 v[24:27], v[128:131], v[226:229], v[24:27]
	v_mfma_f32_16x16x32_bf16 v[56:59], v[132:135], v[226:229], v[56:59]
	v_mfma_f32_16x16x32_bf16 v[88:91], v[136:139], v[226:229], v[88:91]
	v_mfma_f32_16x16x32_bf16 v[120:123], v[140:143], v[226:229], v[120:123]
	v_mfma_f32_16x16x32_bf16 v[28:31], v[128:131], v[230:233], v[28:31]
	v_mfma_f32_16x16x32_bf16 v[60:63], v[132:135], v[230:233], v[60:63]
	v_mfma_f32_16x16x32_bf16 v[92:95], v[136:139], v[230:233], v[92:95]
	v_mfma_f32_16x16x32_bf16 v[124:127], v[140:143], v[230:233], v[124:127]
	ds_read_b128 v[218:221], v245 offset:8192
	ds_read_b128 v[222:225], v245 offset:10240
	ds_read_b128 v[226:229], v245 offset:12288
	ds_read_b128 v[230:233], v245 offset:14336
	s_waitcnt vmcnt(16)
	global_load_dwordx4 v[128:131], v238, s[54:55]
	global_load_dwordx4 v[132:135], v239, s[54:55]
	global_load_dwordx4 v[136:139], v240, s[54:55]
	global_load_dwordx4 v[140:143], v241, s[54:55]
	s_cmp_eq_u32 s59, 31
	s_cbranch_scc1 .Lg2_sww2
	s_add_u32 s54, s54, 1024
	s_addc_u32 s55, s55, 0
	s_branch .Lg2_swdw2

.Lg2_wndw3:
.Lg2_swdw3:
	s_add_i32 s59, s59, 1
	v_add_u32_e32 v244, s56, v242
	v_add_u32_e32 v245, s56, v243
	ds_read_b128 v[200:203], v244 offset:0
	ds_read_b128 v[204:207], v244 offset:2048
	ds_read_b128 v[210:213], v244 offset:4096
	ds_read_b128 v[214:217], v244 offset:6144
	ds_read_b128 v[218:221], v244 offset:8192
	ds_read_b128 v[222:225], v244 offset:10240
	ds_read_b128 v[226:229], v244 offset:12288
	ds_read_b128 v[230:233], v244 offset:14336
	s_waitcnt lgkmcnt(4)
	s_add_i32 m0, s57, s60
	v_mfma_f32_16x16x32_bf16 v[0:3], v[160:163], v[200:203], v[0:3]
	v_mfma_f32_16x16x32_bf16 v[32:35], v[164:167], v[200:203], v[32:35]
	v_mfma_f32_16x16x32_bf16 v[64:67], v[168:171], v[200:203], v[64:67]
	v_mfma_f32_16x16x32_bf16 v[96:99], v[172:175], v[200:203], v[96:99]
	global_load_lds_dwordx4 v234, s[52:53]
	s_add_i32 m0, m0, 0x400
	v_mfma_f32_16x16x32_bf16 v[4:7], v[160:163], v[204:207], v[4:7]
	v_mfma_f32_16x16x32_bf16 v[36:39], v[164:167], v[204:207], v[36:39]
	v_mfma_f32_16x16x32_bf16 v[68:71], v[168:171], v[204:207], v[68:71]
	v_mfma_f32_16x16x32_bf16 v[100:103], v[172:175], v[204:207], v[100:103]
	global_load_lds_dwordx4 v235, s[52:53]
	s_add_i32 m0, m0, 0x400
	v_mfma_f32_16x16x32_bf16 v[8:11], v[160:163], v[210:213], v[8:11]
	v_mfma_f32_16x16x32_bf16 v[40:43], v[164:167], v[210:213], v[40:43]
	v_mfma_f32_16x16x32_bf16 v[72:75], v[168:171], v[210:213], v[72:75]
	v_mfma_f32_16x16x32_bf16 v[104:107], v[172:175], v[210:213], v[104:107]
	global_load_lds_dwordx4 v236, s[52:53]
	s_add_i32 m0, m0, 0x400
	v_mfma_f32_16x16x32_bf16 v[12:15], v[160:163], v[214:217], v[12:15]
	v_mfma_f32_16x16x32_bf16 v[44:47], v[164:167], v[214:217], v[44:47]
	v_mfma_f32_16x16x32_bf16 v[76:79], v[168:171], v[214:217], v[76:79]
	v_mfma_f32_16x16x32_bf16 v[108:111], v[172:175], v[214:217], v[108:111]
	global_load_lds_dwordx4 v237, s[52:53]
	s_cmp_eq_u32 s58, 13
	s_cbranch_scc1 .Lg2_saa4
	s_add_u32 s52, s52, 128
	s_addc_u32 s53, s53, 0
	s_branch .Lg2_sada4

.Lg2_nda4:
.Lg2_sada4:
	ds_read_b128 v[200:203], v245 offset:0
	ds_read_b128 v[204:207], v245 offset:2048
	ds_read_b128 v[210:213], v245 offset:4096
	ds_read_b128 v[214:217], v245 offset:6144
	s_waitcnt lgkmcnt(4)
	v_mfma_f32_16x16x32_bf16 v[16:19], v[160:163], v[218:221], v[16:19]
	v_mfma_f32_16x16x32_bf16 v[48:51], v[164:167], v[218:221], v[48:51]
	v_mfma_f32_16x16x32_bf16 v[80:83], v[168:171], v[218:221], v[80:83]
	v_mfma_f32_16x16x32_bf16 v[112:115], v[172:175], v[218:221], v[112:115]
	v_mfma_f32_16x16x32_bf16 v[20:23], v[160:163], v[222:225], v[20:23]
	v_mfma_f32_16x16x32_bf16 v[52:55], v[164:167], v[222:225], v[52:55]
	v_mfma_f32_16x16x32_bf16 v[84:87], v[168:171], v[222:225], v[84:87]
	v_mfma_f32_16x16x32_bf16 v[116:119], v[172:175], v[222:225], v[116:119]
	v_mfma_f32_16x16x32_bf16 v[24:27], v[160:163], v[226:229], v[24:27]
	v_mfma_f32_16x16x32_bf16 v[56:59], v[164:167], v[226:229], v[56:59]
	v_mfma_f32_16x16x32_bf16 v[88:91], v[168:171], v[226:229], v[88:91]
	v_mfma_f32_16x16x32_bf16 v[120:123], v[172:175], v[226:229], v[120:123]
	v_mfma_f32_16x16x32_bf16 v[28:31], v[160:163], v[230:233], v[28:31]
	v_mfma_f32_16x16x32_bf16 v[60:63], v[164:167], v[230:233], v[60:63]
	v_mfma_f32_16x16x32_bf16 v[92:95], v[168:171], v[230:233], v[92:95]
	v_mfma_f32_16x16x32_bf16 v[124:127], v[172:175], v[230:233], v[124:127]
	ds_read_b128 v[218:221], v245 offset:8192
	ds_read_b128 v[222:225], v245 offset:10240
	ds_read_b128 v[226:229], v245 offset:12288
	ds_read_b128 v[230:233], v245 offset:14336
	s_waitcnt vmcnt(16)
	global_load_dwordx4 v[160:163], v238, s[54:55]
	global_load_dwordx4 v[164:167], v239, s[54:55]
	global_load_dwordx4 v[168:171], v240, s[54:55]
	global_load_dwordx4 v[172:175], v241, s[54:55]
	s_cmp_eq_u32 s59, 31
	s_cbranch_scc1 .Lg2_sww5
	s_add_u32 s54, s54, 1024
	s_addc_u32 s55, s55, 0
	s_branch .Lg2_swdw5

.Lg3_wndw0:
.Lg3_swdw0:
	s_add_i32 s19, s19, 1
	v_add_u32_e32 v244, s16, v242
	v_add_u32_e32 v245, s16, v243
	ds_read_b128 v[198:201], v244 offset:0
	ds_read_b128 v[202:205], v244 offset:2048
	ds_read_b128 v[210:213], v244 offset:4096
	ds_read_b128 v[214:217], v244 offset:6144
	ds_read_b128 v[218:221], v244 offset:8192
	ds_read_b128 v[222:225], v244 offset:10240
	ds_read_b128 v[226:229], v244 offset:12288
	ds_read_b128 v[230:233], v244 offset:14336
	s_waitcnt lgkmcnt(4)
	s_add_i32 m0, s17, s20
	v_mfma_f32_16x16x32_bf16 v[0:3], v[128:131], v[198:201], v[0:3]
	v_mfma_f32_16x16x32_bf16 v[32:35], v[132:135], v[198:201], v[32:35]
	v_mfma_f32_16x16x32_bf16 v[64:67], v[136:139], v[198:201], v[64:67]
	v_mfma_f32_16x16x32_bf16 v[96:99], v[140:143], v[198:201], v[96:99]
	global_load_lds_dwordx4 v234, s[12:13]
	s_add_i32 m0, m0, 0x400
	v_mfma_f32_16x16x32_bf16 v[4:7], v[128:131], v[202:205], v[4:7]
	v_mfma_f32_16x16x32_bf16 v[36:39], v[132:135], v[202:205], v[36:39]
	v_mfma_f32_16x16x32_bf16 v[68:71], v[136:139], v[202:205], v[68:71]
	v_mfma_f32_16x16x32_bf16 v[100:103], v[140:143], v[202:205], v[100:103]
	global_load_lds_dwordx4 v235, s[12:13]
	s_add_i32 m0, m0, 0x400
	v_mfma_f32_16x16x32_bf16 v[8:11], v[128:131], v[210:213], v[8:11]
	v_mfma_f32_16x16x32_bf16 v[40:43], v[132:135], v[210:213], v[40:43]
	v_mfma_f32_16x16x32_bf16 v[72:75], v[136:139], v[210:213], v[72:75]
	v_mfma_f32_16x16x32_bf16 v[104:107], v[140:143], v[210:213], v[104:107]
	global_load_lds_dwordx4 v236, s[12:13]
	s_add_i32 m0, m0, 0x400
	v_mfma_f32_16x16x32_bf16 v[12:15], v[128:131], v[214:217], v[12:15]
	v_mfma_f32_16x16x32_bf16 v[44:47], v[132:135], v[214:217], v[44:47]
	v_mfma_f32_16x16x32_bf16 v[76:79], v[136:139], v[214:217], v[76:79]
	v_mfma_f32_16x16x32_bf16 v[108:111], v[140:143], v[214:217], v[108:111]
	global_load_lds_dwordx4 v237, s[12:13]
	s_cmp_eq_u32 s18, 13
	s_cbranch_scc1 .Lg3_saa1
	s_add_u32 s12, s12, 128
	s_addc_u32 s13, s13, 0
	s_branch .Lg3_sada1

.Lg3_nda1:
.Lg3_sada1:
	ds_read_b128 v[198:201], v245 offset:0
	ds_read_b128 v[202:205], v245 offset:2048
	ds_read_b128 v[210:213], v245 offset:4096
	ds_read_b128 v[214:217], v245 offset:6144
	s_waitcnt lgkmcnt(4)
	v_mfma_f32_16x16x32_bf16 v[16:19], v[128:131], v[218:221], v[16:19]
	v_mfma_f32_16x16x32_bf16 v[48:51], v[132:135], v[218:221], v[48:51]
	v_mfma_f32_16x16x32_bf16 v[80:83], v[136:139], v[218:221], v[80:83]
	v_mfma_f32_16x16x32_bf16 v[112:115], v[140:143], v[218:221], v[112:115]
	v_mfma_f32_16x16x32_bf16 v[20:23], v[128:131], v[222:225], v[20:23]
	v_mfma_f32_16x16x32_bf16 v[52:55], v[132:135], v[222:225], v[52:55]
	v_mfma_f32_16x16x32_bf16 v[84:87], v[136:139], v[222:225], v[84:87]
	v_mfma_f32_16x16x32_bf16 v[116:119], v[140:143], v[222:225], v[116:119]
	v_mfma_f32_16x16x32_bf16 v[24:27], v[128:131], v[226:229], v[24:27]
	v_mfma_f32_16x16x32_bf16 v[56:59], v[132:135], v[226:229], v[56:59]
	v_mfma_f32_16x16x32_bf16 v[88:91], v[136:139], v[226:229], v[88:91]
	v_mfma_f32_16x16x32_bf16 v[120:123], v[140:143], v[226:229], v[120:123]
	v_mfma_f32_16x16x32_bf16 v[28:31], v[128:131], v[230:233], v[28:31]
	v_mfma_f32_16x16x32_bf16 v[60:63], v[132:135], v[230:233], v[60:63]
	v_mfma_f32_16x16x32_bf16 v[92:95], v[136:139], v[230:233], v[92:95]
	v_mfma_f32_16x16x32_bf16 v[124:127], v[140:143], v[230:233], v[124:127]
	ds_read_b128 v[218:221], v245 offset:8192
	ds_read_b128 v[222:225], v245 offset:10240
	ds_read_b128 v[226:229], v245 offset:12288
	ds_read_b128 v[230:233], v245 offset:14336
	s_waitcnt vmcnt(16)
	global_load_dwordx4 v[128:131], v238, s[14:15]
	global_load_dwordx4 v[132:135], v239, s[14:15]
	global_load_dwordx4 v[136:139], v240, s[14:15]
	global_load_dwordx4 v[140:143], v241, s[14:15]
	s_cmp_eq_u32 s19, 31
	s_cbranch_scc1 .Lg3_sww2
	s_add_u32 s14, s14, 1024
	s_addc_u32 s15, s15, 0
	s_branch .Lg3_swdw2

.Lg3_wndw3:
.Lg3_swdw3:
	s_add_i32 s19, s19, 1
	v_add_u32_e32 v244, s16, v242
	v_add_u32_e32 v245, s16, v243
	ds_read_b128 v[198:201], v244 offset:0
	ds_read_b128 v[202:205], v244 offset:2048
	ds_read_b128 v[210:213], v244 offset:4096
	ds_read_b128 v[214:217], v244 offset:6144
	ds_read_b128 v[218:221], v244 offset:8192
	ds_read_b128 v[222:225], v244 offset:10240
	ds_read_b128 v[226:229], v244 offset:12288
	ds_read_b128 v[230:233], v244 offset:14336
	s_waitcnt lgkmcnt(4)
	s_add_i32 m0, s17, s20
	v_mfma_f32_16x16x32_bf16 v[0:3], v[160:163], v[198:201], v[0:3]
	v_mfma_f32_16x16x32_bf16 v[32:35], v[164:167], v[198:201], v[32:35]
	v_mfma_f32_16x16x32_bf16 v[64:67], v[168:171], v[198:201], v[64:67]
	v_mfma_f32_16x16x32_bf16 v[96:99], v[172:175], v[198:201], v[96:99]
	global_load_lds_dwordx4 v234, s[12:13]
	s_add_i32 m0, m0, 0x400
	v_mfma_f32_16x16x32_bf16 v[4:7], v[160:163], v[202:205], v[4:7]
	v_mfma_f32_16x16x32_bf16 v[36:39], v[164:167], v[202:205], v[36:39]
	v_mfma_f32_16x16x32_bf16 v[68:71], v[168:171], v[202:205], v[68:71]
	v_mfma_f32_16x16x32_bf16 v[100:103], v[172:175], v[202:205], v[100:103]
	global_load_lds_dwordx4 v235, s[12:13]
	s_add_i32 m0, m0, 0x400
	v_mfma_f32_16x16x32_bf16 v[8:11], v[160:163], v[210:213], v[8:11]
	v_mfma_f32_16x16x32_bf16 v[40:43], v[164:167], v[210:213], v[40:43]
	v_mfma_f32_16x16x32_bf16 v[72:75], v[168:171], v[210:213], v[72:75]
	v_mfma_f32_16x16x32_bf16 v[104:107], v[172:175], v[210:213], v[104:107]
	global_load_lds_dwordx4 v236, s[12:13]
	s_add_i32 m0, m0, 0x400
	v_mfma_f32_16x16x32_bf16 v[12:15], v[160:163], v[214:217], v[12:15]
	v_mfma_f32_16x16x32_bf16 v[44:47], v[164:167], v[214:217], v[44:47]
	v_mfma_f32_16x16x32_bf16 v[76:79], v[168:171], v[214:217], v[76:79]
	v_mfma_f32_16x16x32_bf16 v[108:111], v[172:175], v[214:217], v[108:111]
	global_load_lds_dwordx4 v237, s[12:13]
	s_cmp_eq_u32 s18, 13
	s_cbranch_scc1 .Lg3_saa4
	s_add_u32 s12, s12, 128
	s_addc_u32 s13, s13, 0
	s_branch .Lg3_sada4

.Lg3_nda4:
.Lg3_sada4:
	ds_read_b128 v[198:201], v245 offset:0
	ds_read_b128 v[202:205], v245 offset:2048
	ds_read_b128 v[210:213], v245 offset:4096
	ds_read_b128 v[214:217], v245 offset:6144
	s_waitcnt lgkmcnt(4)
	v_mfma_f32_16x16x32_bf16 v[16:19], v[160:163], v[218:221], v[16:19]
	v_mfma_f32_16x16x32_bf16 v[48:51], v[164:167], v[218:221], v[48:51]
	v_mfma_f32_16x16x32_bf16 v[80:83], v[168:171], v[218:221], v[80:83]
	v_mfma_f32_16x16x32_bf16 v[112:115], v[172:175], v[218:221], v[112:115]
	v_mfma_f32_16x16x32_bf16 v[20:23], v[160:163], v[222:225], v[20:23]
	v_mfma_f32_16x16x32_bf16 v[52:55], v[164:167], v[222:225], v[52:55]
	v_mfma_f32_16x16x32_bf16 v[84:87], v[168:171], v[222:225], v[84:87]
	v_mfma_f32_16x16x32_bf16 v[116:119], v[172:175], v[222:225], v[116:119]
	v_mfma_f32_16x16x32_bf16 v[24:27], v[160:163], v[226:229], v[24:27]
	v_mfma_f32_16x16x32_bf16 v[56:59], v[164:167], v[226:229], v[56:59]
	v_mfma_f32_16x16x32_bf16 v[88:91], v[168:171], v[226:229], v[88:91]
	v_mfma_f32_16x16x32_bf16 v[120:123], v[172:175], v[226:229], v[120:123]
	v_mfma_f32_16x16x32_bf16 v[28:31], v[160:163], v[230:233], v[28:31]
	v_mfma_f32_16x16x32_bf16 v[60:63], v[164:167], v[230:233], v[60:63]
	v_mfma_f32_16x16x32_bf16 v[92:95], v[168:171], v[230:233], v[92:95]
	v_mfma_f32_16x16x32_bf16 v[124:127], v[172:175], v[230:233], v[124:127]
	ds_read_b128 v[218:221], v245 offset:8192
	ds_read_b128 v[222:225], v245 offset:10240
	ds_read_b128 v[226:229], v245 offset:12288
	ds_read_b128 v[230:233], v245 offset:14336
	s_waitcnt vmcnt(16)
	global_load_dwordx4 v[160:163], v238, s[14:15]
	global_load_dwordx4 v[164:167], v239, s[14:15]
	global_load_dwordx4 v[168:171], v240, s[14:15]
	global_load_dwordx4 v[172:175], v241, s[14:15]
	s_cmp_eq_u32 s19, 31
	s_cbranch_scc1 .Lg3_sww5
	s_add_u32 s14, s14, 1024
	s_addc_u32 s15, s15, 0
	s_branch .Lg3_swdw5
